# speedup vs baseline: 1.1204x; 1.0094x over previous
;     ...
;   for (int i = 0; i < MS / 2; ++i) ap[i] = arow(lrow + 64 * i) + lc;
;   const long brs = (b_rs < 0) ? ldb : b_rs;
;   const u16* bp0 = ((b_rs < 0) ? Bt + (long)n0 * ldb : Bt) + (long)lrow * brs + lc;
;   const u16* bp1 = bp0 + 64 * brs;
;   asm volatile("" : "+v"(bp0), "+v"(bp1));
;   const int nk = nk64 * 2;
;   const int wbase = __builtin_amdgcn_readfirstlane(wid) * 1024;
;   const int rg = (l15 >> 2) & 3;
;   const int gr = (rg == 0) ? 0 : (rg == 1) ? 2 : (rg == 2) ? 3 : 1;
;   const int aoff_r = (wm * (MS * 16) + l15) * 64 + ((quad ^ gr) << 4);
;   const int boff_r = A_BYTES + (wn * 64 + l15) * 64 + ((quad ^ gr) << 4);
;     ...
;   if (!prefetched) {
;     ISSUE(0)
;     ISSUE(1)
;     if (NST == 4) ISSUE(2)
;   }
; template <int MS>
; DEV void zero_acc(f32x4 (&acc)[MS][4]) {
; #pragma unroll
;   for (int a = 0; a < MS; ++a)
; #pragma unroll
;     for (int b = 0; b < 4; ++b) acc[a][b] = f32x4{0.f, 0.f, 0.f, 0.f};
.LBB0_206:
	s_or_b64 exec, exec, s[4:5]
	s_lshl_b32 s2, s2, 3
	v_readlane_b32 s4, v252, 11
	s_add_i32 s2, s2, s4
	s_and_b32 s4, s18, 7
	s_or_b32 s2, s2, s4
	s_lshl_b32 s12, s2, 8
	s_ashr_i32 s13, s12, 31
	s_lshl_b64 s[4:5], s[12:13], 11
	s_add_u32 s4, s42, s4
	s_addc_u32 s5, s43, s5
	v_lshlrev_b32_e32 v0, 1, v8
	v_lshl_add_u64 v[12:13], s[4:5], 0, v[0:1]
	v_lshlrev_b64 v[6:7], 6, v[6:7]
	s_mov_b64 s[4:5], 0x1000
	v_lshl_add_u64 v[192:193], v[6:7], 0, s[4:5]
	s_mov_b64 s[4:5], 0x3000
	v_lshl_add_u64 v[194:195], v[6:7], 0, s[76:77]
	v_lshl_add_u64 v[196:197], v[6:7], 0, s[4:5]
	s_lshl_b32 s13, s15, 10
	v_lshl_add_u64 v[198:199], v[12:13], 0, v[190:191]
	v_lshl_add_u64 v[200:201], v[12:13], 0, v[192:193]
	v_lshl_add_u64 v[202:203], v[12:13], 0, v[194:195]
	s_cmp_lg_u32 s18, s35
	v_lshl_add_u64 v[204:205], v[12:13], 0, v[196:197]
	s_cbranch_scc1 .LBB0_208
	s_mov_b32 m0, s13
	s_mov_b64 s[4:5], 0x4000
	global_load_lds_dwordx4 v[198:199], off
	s_add_i32 m0, s13, 0x1000
	v_lshl_add_u64 v[6:7], v[198:199], 0, s[4:5]
	global_load_lds_dwordx4 v[200:201], off
	s_add_i32 m0, s13, 0x2000
	s_nop 0
	global_load_lds_dwordx4 v[202:203], off
	s_add_i32 m0, s13, 0x3000
	s_nop 0
	global_load_lds_dwordx4 v[204:205], off
	s_add_i32 m0, s13, 0x4000
	s_nop 0
	global_load_lds_dwordx4 v[2:3], off
	s_add_i32 m0, s13, 0x5000
	s_nop 0
	global_load_lds_dwordx4 v[4:5], off
	s_add_i32 m0, s13, 0x6000
	s_nop 0
	global_load_lds_dwordx4 v[6:7], off
	v_lshl_add_u64 v[6:7], v[200:201], 0, s[4:5]
	s_add_i32 m0, s13, 0x7000
	s_nop 0
	global_load_lds_dwordx4 v[6:7], off
	v_lshl_add_u64 v[6:7], v[202:203], 0, s[4:5]
	s_add_i32 m0, s13, 0x8000
	s_nop 0
	global_load_lds_dwordx4 v[6:7], off
	v_lshl_add_u64 v[6:7], v[204:205], 0, s[4:5]
	s_add_i32 m0, s13, 0x9000
	s_nop 0
	global_load_lds_dwordx4 v[6:7], off
	v_lshl_add_u64 v[6:7], v[2:3], 0, s[76:77]
	s_add_i32 m0, s13, 0xa000
	s_nop 0
	global_load_lds_dwordx4 v[6:7], off
	v_lshl_add_u64 v[6:7], v[4:5], 0, s[76:77]
	s_add_i32 m0, s13, 0xb000
	s_nop 0
	global_load_lds_dwordx4 v[6:7], off
	s_waitcnt vmcnt(0)
.LBB0_208:
	s_mov_b64 s[4:5], 0x4000
	v_lshlrev_b32_e32 v6, 6, v9
	v_lshl_add_u64 v[208:209], v[2:3], 0, s[4:5]
	v_mov_b32_e32 v2, 0
	v_and_b32_e32 v187, 0xffffe3c0, v6
	v_bitop3_b32 v189, v10, v9, 48 bitop3:0x78
	v_and_b32_e32 v238, 0x13c0, v6
	v_lshl_add_u64 v[206:207], v[4:5], 0, s[4:5]
	s_mov_b64 s[4:5], 0
	s_mov_b32 s15, 2
	s_mov_b32 s19, 0
	s_mov_b32 s20, 0
	v_mov_b32_e32 v3, v2
	v_mov_b32_e32 v4, v2
	v_mov_b32_e32 v5, v2
	v_mov_b32_e32 v6, v2
	v_mov_b32_e32 v7, v2
	v_mov_b32_e32 v8, v2
	v_mov_b32_e32 v9, v2
	v_mov_b32_e32 v10, v2
	v_mov_b32_e32 v11, v2
	v_mov_b32_e32 v12, v2
	v_mov_b32_e32 v13, v2
	v_mov_b32_e32 v14, v2
	v_mov_b32_e32 v15, v2
	v_mov_b32_e32 v16, v2
	v_mov_b32_e32 v17, v2
	v_mov_b32_e32 v18, v2
	v_mov_b32_e32 v19, v2
	v_mov_b32_e32 v20, v2
	v_mov_b32_e32 v21, v2
	v_mov_b32_e32 v22, v2
	v_mov_b32_e32 v23, v2
	v_mov_b32_e32 v24, v2
	v_mov_b32_e32 v25, v2
	v_mov_b32_e32 v26, v2
	v_mov_b32_e32 v27, v2
	v_mov_b32_e32 v28, v2
	v_mov_b32_e32 v29, v2
	v_mov_b32_e32 v30, v2
	v_mov_b32_e32 v31, v2
	v_mov_b32_e32 v32, v2
	v_mov_b32_e32 v33, v2
	v_mov_b32_e32 v34, v2
	v_mov_b32_e32 v35, v2
	v_mov_b32_e32 v36, v2
	v_mov_b32_e32 v37, v2
	v_mov_b32_e32 v38, v2
	v_mov_b32_e32 v39, v2
	v_mov_b32_e32 v40, v2
	v_mov_b32_e32 v41, v2
	v_mov_b32_e32 v42, v2
	v_mov_b32_e32 v43, v2
	v_mov_b32_e32 v44, v2
	v_mov_b32_e32 v45, v2
	v_mov_b32_e32 v46, v2
	v_mov_b32_e32 v47, v2
	v_mov_b32_e32 v48, v2
	v_mov_b32_e32 v49, v2
	v_mov_b32_e32 v50, v2
	v_mov_b32_e32 v51, v2
	v_mov_b32_e32 v52, v2
	v_mov_b32_e32 v53, v2
	v_mov_b32_e32 v54, v2
	v_mov_b32_e32 v55, v2
	v_mov_b32_e32 v56, v2
	v_mov_b32_e32 v57, v2
	v_mov_b32_e32 v58, v2
	v_mov_b32_e32 v59, v2
	v_mov_b32_e32 v60, v2
	v_mov_b32_e32 v61, v2
	v_mov_b32_e32 v62, v2
	v_mov_b32_e32 v63, v2
	v_mov_b32_e32 v64, v2
	v_mov_b32_e32 v65, v2
	v_mov_b32_e32 v66, v2
	v_mov_b32_e32 v67, v2
	v_mov_b32_e32 v68, v2
	v_mov_b32_e32 v69, v2
	v_mov_b32_e32 v70, v2
	v_mov_b32_e32 v71, v2
	v_mov_b32_e32 v72, v2
	v_mov_b32_e32 v73, v2
	v_mov_b32_e32 v74, v2
	v_mov_b32_e32 v75, v2
	v_mov_b32_e32 v76, v2
	v_mov_b32_e32 v77, v2
	v_mov_b32_e32 v78, v2
	v_mov_b32_e32 v79, v2
	v_mov_b32_e32 v80, v2
	v_mov_b32_e32 v81, v2
	v_mov_b32_e32 v82, v2
	v_mov_b32_e32 v83, v2
	v_mov_b32_e32 v84, v2
	v_mov_b32_e32 v85, v2
	v_mov_b32_e32 v86, v2
	v_mov_b32_e32 v87, v2
	v_mov_b32_e32 v88, v2
	v_mov_b32_e32 v89, v2
	v_mov_b32_e32 v90, v2
	v_mov_b32_e32 v91, v2
	v_mov_b32_e32 v92, v2
	v_mov_b32_e32 v93, v2
	v_mov_b32_e32 v94, v2
	v_mov_b32_e32 v95, v2
	v_mov_b32_e32 v96, v2
	v_mov_b32_e32 v97, v2
	v_mov_b32_e32 v98, v2
	v_mov_b32_e32 v99, v2
	v_mov_b32_e32 v100, v2
	v_mov_b32_e32 v101, v2
	v_mov_b32_e32 v102, v2
	v_mov_b32_e32 v103, v2
	v_mov_b32_e32 v104, v2
	v_mov_b32_e32 v105, v2
	v_mov_b32_e32 v106, v2
	v_mov_b32_e32 v107, v2
	v_mov_b32_e32 v108, v2
	v_mov_b32_e32 v109, v2
	v_mov_b32_e32 v110, v2
	v_mov_b32_e32 v111, v2
	v_mov_b32_e32 v112, v2
	v_mov_b32_e32 v113, v2
	v_mov_b32_e32 v114, v2
	v_mov_b32_e32 v115, v2
	v_mov_b32_e32 v116, v2
	v_mov_b32_e32 v117, v2
	v_mov_b32_e32 v118, v2
	v_mov_b32_e32 v119, v2
	v_mov_b32_e32 v120, v2
	v_mov_b32_e32 v121, v2
	v_mov_b32_e32 v122, v2
	v_mov_b32_e32 v123, v2
	v_mov_b32_e32 v124, v2
	v_mov_b32_e32 v125, v2
	v_mov_b32_e32 v126, v2
	v_mov_b32_e32 v127, v2
	v_mov_b32_e32 v128, v2
	v_mov_b32_e32 v129, v2
	s_branch .LBB0_210

;     ...
;   for (int kt = 0; kt < nk; ++kt) {
;     if (NST == 4 && kt + 2 < nk) asm volatile("s_waitcnt vmcnt(%0)" ::"n"(2 * NLD) : "memory");
;     else if (kt + 1 < nk) asm volatile("s_waitcnt vmcnt(%0)" ::"n"(NLD) : "memory");
;     else asm volatile("s_waitcnt vmcnt(0)" ::: "memory");
;     __builtin_amdgcn_s_barrier();
.LBB0_212:
	s_andn2_b64 vcc, exec, s[10:11]
	s_cbranch_vccnz .LBB0_214
	s_cmp_lt_u32 s2, 2
	s_cbranch_scc1 .Ldrain_early_f1
	s_waitcnt vmcnt(6)
	s_branch .LBB0_214
.Ldrain_early_f1:
	s_waitcnt vmcnt(63)

;     ...
;   for (int i = 0; i < MS / 2; ++i) ap[i] = arow(lrow + 64 * i) + lc;
;   const long brs = (b_rs < 0) ? ldb : b_rs;
;   const u16* bp0 = ((b_rs < 0) ? Bt + (long)n0 * ldb : Bt) + (long)lrow * brs + lc;
;   const u16* bp1 = bp0 + 64 * brs;
;   asm volatile("" : "+v"(bp0), "+v"(bp1));
;   const int nk = nk64 * 2;
;   const int wbase = __builtin_amdgcn_readfirstlane(wid) * 1024;
;   const int rg = (l15 >> 2) & 3;
;   const int gr = (rg == 0) ? 0 : (rg == 1) ? 2 : (rg == 2) ? 3 : 1;
;   const int aoff_r = (wm * (MS * 16) + l15) * 64 + ((quad ^ gr) << 4);
;   const int boff_r = A_BYTES + (wn * 64 + l15) * 64 + ((quad ^ gr) << 4);
;     ...
;   if (!prefetched) {
;     ISSUE(0)
;     ISSUE(1)
;     if (NST == 4) ISSUE(2)
;   }
.LBB0_2333:
	s_or_b64 exec, exec, s[4:5]
	s_lshl_b32 s2, s2, 3
	v_readlane_b32 s4, v252, 11
	s_add_i32 s2, s2, s4
	s_and_b32 s4, s14, 7
	s_or_b32 s2, s2, s4
	s_lshl_b32 s10, s2, 8
	s_ashr_i32 s11, s10, 31
	s_lshl_b64 s[4:5], s[10:11], 11
	s_add_u32 s4, s88, s4
	s_addc_u32 s5, s89, s5
	v_lshlrev_b32_e32 v0, 1, v8
	v_lshl_add_u64 v[12:13], s[4:5], 0, v[0:1]
	v_lshlrev_b64 v[6:7], 6, v[6:7]
	s_mov_b64 s[4:5], 0x1000
	v_lshl_add_u64 v[192:193], v[6:7], 0, s[4:5]
	s_mov_b64 s[4:5], 0x3000
	v_lshl_add_u64 v[194:195], v[6:7], 0, s[76:77]
	v_lshl_add_u64 v[196:197], v[6:7], 0, s[4:5]
	s_lshl_b32 s11, s13, 10
	v_lshl_add_u64 v[198:199], v[12:13], 0, v[190:191]
	v_lshl_add_u64 v[200:201], v[12:13], 0, v[192:193]
	v_lshl_add_u64 v[202:203], v[12:13], 0, v[194:195]
	s_cmp_lg_u32 s14, s35
	v_lshl_add_u64 v[204:205], v[12:13], 0, v[196:197]
	s_cbranch_scc1 .LBB0_2335
	s_mov_b32 m0, s11
	s_mov_b64 s[4:5], 0x4000
	global_load_lds_dwordx4 v[198:199], off
	s_add_i32 m0, s11, 0x1000
	v_lshl_add_u64 v[6:7], v[198:199], 0, s[4:5]
	global_load_lds_dwordx4 v[200:201], off
	s_add_i32 m0, s11, 0x2000
	s_nop 0
	global_load_lds_dwordx4 v[202:203], off
	s_add_i32 m0, s11, 0x3000
	s_nop 0
	global_load_lds_dwordx4 v[204:205], off
	s_add_i32 m0, s11, 0x4000
	s_nop 0
	global_load_lds_dwordx4 v[2:3], off
	s_add_i32 m0, s11, 0x5000
	s_nop 0
	global_load_lds_dwordx4 v[4:5], off
	s_add_i32 m0, s11, 0x6000
	s_nop 0
	global_load_lds_dwordx4 v[6:7], off
	v_lshl_add_u64 v[6:7], v[200:201], 0, s[4:5]
	s_add_i32 m0, s11, 0x7000
	s_nop 0
	global_load_lds_dwordx4 v[6:7], off
	v_lshl_add_u64 v[6:7], v[202:203], 0, s[4:5]
	s_add_i32 m0, s11, 0x8000
	s_nop 0
	global_load_lds_dwordx4 v[6:7], off
	v_lshl_add_u64 v[6:7], v[204:205], 0, s[4:5]
	s_add_i32 m0, s11, 0x9000
	s_nop 0
	global_load_lds_dwordx4 v[6:7], off
	v_lshl_add_u64 v[6:7], v[2:3], 0, s[76:77]
	s_add_i32 m0, s11, 0xa000
	s_nop 0
	global_load_lds_dwordx4 v[6:7], off
	v_lshl_add_u64 v[6:7], v[4:5], 0, s[76:77]
	s_add_i32 m0, s11, 0xb000
	s_nop 0
	global_load_lds_dwordx4 v[6:7], off
	s_waitcnt vmcnt(0)

;     ...
;   for (int kt = 0; kt < nk; ++kt) {
;     if (NST == 4 && kt + 2 < nk) asm volatile("s_waitcnt vmcnt(%0)" ::"n"(2 * NLD) : "memory");
;     else if (kt + 1 < nk) asm volatile("s_waitcnt vmcnt(%0)" ::"n"(NLD) : "memory");
;     else asm volatile("s_waitcnt vmcnt(0)" ::: "memory");
;     __builtin_amdgcn_s_barrier();
.LBB0_2339:
	s_andn2_b64 vcc, exec, s[8:9]
	s_cbranch_vccnz .LBB0_2341
	s_cmp_lt_u32 s2, 2
	s_cbranch_scc1 .Ldrain_early_f2
	s_waitcnt vmcnt(6)
	s_branch .LBB0_2341
